# speedup vs baseline: 1.0103x; 1.0034x over previous
; __device__ __forceinline__ unsigned xb_ld(unsigned* p)              { return __hip_atomic_load(p, __ATOMIC_RELAXED, __HIP_MEMORY_SCOPE_AGENT); }
; __device__ __forceinline__ unsigned xb_add(unsigned* p, unsigned v) { return __hip_atomic_fetch_add(p, v, __ATOMIC_RELAXED, __HIP_MEMORY_SCOPE_AGENT); }
; #define XB_SPIN(cond, bar) do { unsigned _sp = 0; while (cond) { __builtin_amdgcn_s_sleep(1); \
;     if ((++_sp & 255u) == 0u) { if (xb_ld(&(bar)[XB_TMO])) break; if (_sp > XB_SPIN_CAP) { atomicAdd(&(bar)[XB_TMO], 1u); break; } } } } while (0)
; __device__ __forceinline__ void xcd_barrier(const XcdBarrier& b) {
;     ...
;         const unsigned old = xb_add(&bar[XB_XSUB(b.x)], 1u);
;         const unsigned gen = old / nloc;
;         if (old + 1u == (gen + 1u) * nloc) {
;             __builtin_amdgcn_fence(__ATOMIC_RELEASE, "agent");
;             asm volatile("s_waitcnt vmcnt(0)" ::: "memory");
;             const unsigned og = xb_add(&bar[XB_TOP], 1u);
;             const unsigned tg = og / nx;
;             if (og + 1u == (tg + 1u) * nx) xb_add(&bar[XB_TOPGEN], 1u);
;             else XB_SPIN(xb_ld(&bar[XB_TOPGEN]) == tg, bar);
;             __builtin_amdgcn_fence(__ATOMIC_ACQUIRE, "agent");
;             xb_add(&bar[XB_XGEN(b.x)], 1u);
;             asm volatile("s_waitcnt vmcnt(0)" ::: "memory");
.LBB0_120:
	s_or_b64 exec, exec, s[0:1]
	v_mov_b32_e32 v0, s23
	v_add_co_u32_e32 v2, vcc, 0x2000, v0
	v_mov_b32_e32 v0, s22
	s_nop 0
	v_addc_co_u32_e32 v3, vcc, 0, v0, vcc
	s_waitcnt vmcnt(0) lgkmcnt(0)
	flat_atomic_add v[2:3], v230 offset:1024
	buffer_inv sc1
	s_waitcnt vmcnt(0)
